# v28 plus: FE block before the K/V load wait in half-step 1; O-store ladder preloads the 16 row denominators with one wait; sinks value via scalar load
# speedup vs baseline: 1.0024x; 1.0024x over previous
.LBB0_519:
	s_andn2_b64 vcc, exec, s[0:1]
	s_cbranch_vccnz .LBB0_729
	s_add_i32 s0, s9, 0xfffffc80
	s_lshr_b32 s86, s0, 7
	s_lshl_b32 s10, s9, 8
	s_lshl_b64 s[0:1], s[86:87], 12
	s_and_b32 s29, s10, 0xf00
	s_bfe_u32 s8, s9, 0x30004
	s_or_b32 s0, s0, s29
	s_mul_i32 s11, s86, 0xa400000
	s_mul_hi_u32 s10, s86, 0xa400000
	s_add_u32 s11, s88, s11
	s_addc_u32 s10, s89, s10
	s_lshl_b32 s22, s9, 2
	s_and_b32 s22, s22, 0x100
	s_add_u32 s11, s11, s22
	s_addc_u32 s10, s10, 0
	s_add_u32 s22, s11, 0x2c00
	s_addc_u32 s23, s10, 0
	s_add_u32 s76, s11, 0x2e00
	s_addc_u32 s77, s10, 0
	s_mul_i32 s10, s0, 0x2800
	s_mul_hi_u32 s0, s0, 0x2800
	s_mulk_i32 s1, 0x2800
	s_add_i32 s0, s0, s1
	s_add_u32 s1, s85, s10
	s_addc_u32 s0, s13, s0
	s_lshl_b32 s10, s8, 8
	s_add_u32 s1, s1, s10
	s_addc_u32 s0, s0, 0
	s_add_u32 s42, s1, 0xc00
	s_addc_u32 s43, s0, 0
	s_lshl_b32 s0, s8, 23
	s_sub_i32 s61, 0x40b504f3, s0
	s_or_b32 s0, s8, s81
	s_ashr_i32 s1, s0, 31
	v_readlane_b32 s44, v254, 47
	s_lshl_b64 s[0:1], s[0:1], 2
	v_readlane_b32 s56, v254, 59
	v_readlane_b32 s57, v254, 60
	s_add_u32 s0, s56, s0
	s_addc_u32 s1, s57, s1
	s_load_dword s0, s[0:1], 0x0
	v_readlane_b32 s48, v254, 51
	v_readlane_b32 s49, v254, 52
	v_readlane_b32 s53, v254, 56
	v_readlane_b32 s48, v255, 22
	v_readlane_b32 s45, v254, 48
	v_readlane_b32 s46, v254, 49
	v_readlane_b32 s47, v254, 50
	v_readlane_b32 s50, v254, 53
	v_readlane_b32 s51, v254, 54
	v_readlane_b32 s52, v254, 55
	v_readlane_b32 s54, v254, 57
	v_readlane_b32 s55, v254, 58
	v_readlane_b32 s58, v254, 61
	v_readlane_b32 s59, v254, 62
	v_readlane_b32 s49, v255, 23
	s_mov_b32 s8, 1.0
	s_movk_i32 s53, 0x80
	s_mov_b32 s38, 64
	s_movk_i32 s66, 0x5200
	s_waitcnt lgkmcnt(0)
	v_mov_b32_e32 v0, 0x413504f3
	s_nop 0
	v_mul_f32_e32 v14, s0, v0
	s_mov_b64 s[0:1], 0
	s_cbranch_execz .LBB0_522
	s_branch .LBB0_730

.LBB0_559:
	v_max_f32_e32 v17, v117, v117
	v_max_f32_e32 v18, v116, v116
	v_max_f32_e32 v17, v18, v17
	v_max3_f32 v17, v17, v118, v119
	v_max3_f32 v17, v17, v120, v121
	v_max3_f32 v17, v17, v122, v123
	v_max3_f32 v17, v17, v124, v125
	v_max3_f32 v17, v17, v126, v127
	v_max3_f32 v17, v17, v128, v129
	v_max3_f32 v17, v17, v130, v131
	v_max3_f32 v17, v17, v100, v101
	v_max3_f32 v17, v17, v102, v103
	v_max3_f32 v17, v17, v104, v105
	v_max3_f32 v17, v17, v106, v107
	v_max3_f32 v17, v17, v108, v109
	v_max3_f32 v17, v17, v110, v111
	v_max3_f32 v17, v17, v112, v113
	v_max3_f32 v17, v17, v114, v115
	v_mov_b32_e32 v18, v17
	s_nop 1
	v_permlane32_swap_b32_e32 v17, v18
	v_max_f32_e32 v18, v18, v18
	v_max_f32_e32 v17, v17, v17
	v_max_f32_e32 v17, v17, v18
	v_sub_f32_e32 v18, v17, v196
	v_mul_f32_e32 v18, 0x3db504f3, v18
	v_cmp_ge_f32_e32 vcc, s34, v18
	v_max_f32_e32 v18, v196, v196
	v_max_f32_e32 v17, v18, v17
	v_sub_f32_e32 v18, v196, v17
	v_mul_f32_e32 v18, 0x3e0293ee, v18
	v_exp_f32_e32 v18, v18
	s_cmp_eq_u64 vcc, exec
	s_cselect_b64 s[0:1], -1, 0
	s_barrier
	v_cndmask_b32_e64 v240, v18, 1.0, s[0:1]
	v_cmp_gt_f32_e32 vcc, 1.0, v240
	v_cndmask_b32_e64 v241, v17, v196, s[0:1]
	v_mul_f32_e32 v196, 0xbe0293ee, v241
	v_fmamk_f32 v17, v116, 0x3e0293ee, v196
	v_fmamk_f32 v18, v117, 0x3e0293ee, v196
	v_fmamk_f32 v19, v118, 0x3e0293ee, v196
	v_fmamk_f32 v20, v119, 0x3e0293ee, v196
	v_fmamk_f32 v21, v120, 0x3e0293ee, v196
	v_fmamk_f32 v22, v121, 0x3e0293ee, v196
	v_fmamk_f32 v23, v122, 0x3e0293ee, v196
	v_fmamk_f32 v24, v123, 0x3e0293ee, v196
	v_fmamk_f32 v25, v124, 0x3e0293ee, v196
	v_fmamk_f32 v26, v125, 0x3e0293ee, v196
	v_fmamk_f32 v27, v126, 0x3e0293ee, v196
	v_fmamk_f32 v28, v127, 0x3e0293ee, v196
	v_fmamk_f32 v29, v128, 0x3e0293ee, v196
	v_fmamk_f32 v30, v129, 0x3e0293ee, v196
	v_fmamk_f32 v31, v130, 0x3e0293ee, v196
	v_fmamk_f32 v128, v131, 0x3e0293ee, v196
	v_fmamk_f32 v116, v100, 0x3e0293ee, v196
	v_fmamk_f32 v117, v101, 0x3e0293ee, v196
	v_fmamk_f32 v118, v102, 0x3e0293ee, v196
	v_fmamk_f32 v119, v103, 0x3e0293ee, v196
	v_fmamk_f32 v120, v104, 0x3e0293ee, v196
	v_fmamk_f32 v121, v105, 0x3e0293ee, v196
	v_fmamk_f32 v122, v106, 0x3e0293ee, v196
	v_fmamk_f32 v123, v107, 0x3e0293ee, v196
	v_fmamk_f32 v124, v108, 0x3e0293ee, v196
	v_fmamk_f32 v125, v109, 0x3e0293ee, v196
	v_fmamk_f32 v126, v110, 0x3e0293ee, v196
	v_fmamk_f32 v127, v111, 0x3e0293ee, v196
	v_exp_f32_e32 v96, v17
	v_exp_f32_e32 v97, v18
	v_exp_f32_e32 v98, v19
	v_exp_f32_e32 v99, v20
	v_exp_f32_e32 v100, v21
	v_exp_f32_e32 v101, v22
	v_exp_f32_e32 v102, v23
	v_exp_f32_e32 v103, v24
	v_exp_f32_e32 v104, v25
	v_exp_f32_e32 v105, v26
	v_exp_f32_e32 v106, v27
	v_exp_f32_e32 v107, v28
	v_exp_f32_e32 v108, v29
	v_exp_f32_e32 v109, v30
	v_exp_f32_e32 v110, v31
	v_exp_f32_e32 v111, v128
	v_fmamk_f32 v198, v112, 0x3e0293ee, v196
	v_fmamk_f32 v199, v113, 0x3e0293ee, v196
	v_fmamk_f32 v242, v114, 0x3e0293ee, v196
	v_fmac_f32_e32 v196, 0x3e0293ee, v115
	s_waitcnt vmcnt(0)
	s_waitcnt vmcnt(3)
	ds_write_b128 v231, v[2:5]
	s_waitcnt vmcnt(2)
	ds_write_b128 v232, v[6:9]
	s_waitcnt vmcnt(1)
	ds_write_b128 v221, v[10:13] offset:32768
	s_waitcnt vmcnt(0)
	ds_write_b128 v221, v[192:195] offset:40960
	s_cbranch_vccz .Lfe1_done
	s_and_saveexec_b64 s[78:79], s[38:39]
	ds_write_b32 v223, v240 offset:128
	s_or_b64 exec, exec, s[78:79]
	s_waitcnt lgkmcnt(0)
	ds_read_b128 v[18:21], v217 offset:224
	ds_read_b128 v[22:25], v217 offset:192
	ds_read_b128 v[26:29], v217 offset:160
	ds_read_b128 v[2:5], v217 offset:128
	s_waitcnt lgkmcnt(3)
	v_pk_mul_f32 v[94:95], v[94:95], v[20:21]
	s_waitcnt lgkmcnt(2)
	v_pk_mul_f32 v[90:91], v[90:91], v[24:25]
	s_waitcnt lgkmcnt(1)
	v_pk_mul_f32 v[86:87], v[86:87], v[28:29]
	s_waitcnt lgkmcnt(0)
	v_pk_mul_f32 v[82:83], v[82:83], v[4:5]
	v_pk_mul_f32 v[92:93], v[92:93], v[18:19]
	v_pk_mul_f32 v[88:89], v[88:89], v[22:23]
	v_pk_mul_f32 v[84:85], v[84:85], v[26:27]
	v_pk_mul_f32 v[80:81], v[80:81], v[2:3]
	v_pk_mul_f32 v[78:79], v[78:79], v[20:21]
	v_pk_mul_f32 v[74:75], v[74:75], v[24:25]
	v_pk_mul_f32 v[70:71], v[70:71], v[28:29]
	v_pk_mul_f32 v[66:67], v[66:67], v[4:5]
	v_pk_mul_f32 v[76:77], v[76:77], v[18:19]
	v_pk_mul_f32 v[72:73], v[72:73], v[22:23]
	v_pk_mul_f32 v[68:69], v[68:69], v[26:27]
	v_pk_mul_f32 v[64:65], v[64:65], v[2:3]
	v_pk_mul_f32 v[62:63], v[62:63], v[20:21]
	v_pk_mul_f32 v[58:59], v[58:59], v[24:25]
	v_pk_mul_f32 v[54:55], v[54:55], v[28:29]
	v_pk_mul_f32 v[50:51], v[50:51], v[4:5]
	v_pk_mul_f32 v[60:61], v[60:61], v[18:19]
	v_pk_mul_f32 v[56:57], v[56:57], v[22:23]
	v_pk_mul_f32 v[52:53], v[52:53], v[26:27]
	v_pk_mul_f32 v[48:49], v[48:49], v[2:3]
	v_pk_mul_f32 v[46:47], v[46:47], v[20:21]
	v_pk_mul_f32 v[42:43], v[42:43], v[24:25]
	v_pk_mul_f32 v[38:39], v[38:39], v[28:29]
	v_pk_mul_f32 v[34:35], v[34:35], v[4:5]
	v_pk_mul_f32 v[44:45], v[44:45], v[18:19]
	v_pk_mul_f32 v[40:41], v[40:41], v[22:23]
	v_pk_mul_f32 v[36:37], v[36:37], v[26:27]
	v_pk_mul_f32 v[32:33], v[32:33], v[2:3]
.Lfe1_done:
	s_waitcnt lgkmcnt(0)
	s_barrier
	s_cmp_gt_i32 s8, s59
	s_cselect_b64 s[0:1], -1, 0
	s_add_i32 s9, s29, -1
	s_cmp_le_i32 s9, s60
	s_cselect_b64 s[78:79], -1, 0
	s_or_b64 s[0:1], s[0:1], s[78:79]
	s_and_b64 vcc, exec, s[0:1]
	v_readfirstlane_b32 s78, v252
	s_nop 0
	s_cmpk_ge_u32 s78, 0x100
	s_cbranch_scc1 .Lst2_b
	s_cbranch_vccnz .LBB0_565
	v_subrev_u32_e32 v17, 64, v197
	v_cvt_f32_i32_e32 v17, v17
	ds_read_b128 v[18:21], v235 offset:32768
	v_mov_b32_e32 v205, v204
	v_fma_f32 v145, s61, v17, s61
	v_add_f32_e32 v146, s61, v145
	v_mul_f32_e32 v144, s61, v17
	v_add_f32_e32 v147, s61, v146
	v_pk_add_f32 v[148:149], v[206:207], v[144:145]
	v_pk_add_f32 v[150:151], v[206:207], v[146:147]
	v_pk_add_f32 v[152:153], v[206:207], v[148:149]
	v_pk_add_f32 v[154:155], v[206:207], v[150:151]
	v_pk_add_f32 v[156:157], v[206:207], v[152:153]
	v_pk_add_f32 v[158:159], v[206:207], v[154:155]
	v_pk_add_f32 v[128:129], v[14:15], v[144:145]
	v_pk_add_f32 v[132:133], v[204:205], v[148:149]
	v_pk_add_f32 v[136:137], v[204:205], v[152:153]
	v_pk_add_f32 v[130:131], v[204:205], v[146:147]
	v_pk_add_f32 v[140:141], v[204:205], v[156:157]
	v_pk_add_f32 v[134:135], v[204:205], v[150:151]
	v_pk_add_f32 v[138:139], v[204:205], v[154:155]
	v_pk_add_f32 v[142:143], v[204:205], v[158:159]
	s_waitcnt lgkmcnt(0)
	v_mfma_f32_32x32x16_bf16 v[144:159], v[18:21], v[188:191], v[144:159]
	ds_read_b128 v[18:21], v235 offset:40960
	s_waitcnt lgkmcnt(0)
	v_mfma_f32_32x32x16_bf16 v[128:143], v[18:21], v[188:191], v[128:143]
	ds_read_b128 v[18:21], v236 offset:32768
	s_waitcnt lgkmcnt(0)
	v_mfma_f32_32x32x16_bf16 v[144:159], v[18:21], v[184:187], v[144:159]
	ds_read_b128 v[18:21], v236 offset:40960
	s_waitcnt lgkmcnt(0)
	v_mfma_f32_32x32x16_bf16 v[128:143], v[18:21], v[184:187], v[128:143]
	ds_read_b128 v[18:21], v237 offset:32768
	s_waitcnt lgkmcnt(0)
	v_mfma_f32_32x32x16_bf16 v[144:159], v[18:21], v[180:183], v[144:159]
	ds_read_b128 v[18:21], v237 offset:40960
	s_waitcnt lgkmcnt(0)
	v_mfma_f32_32x32x16_bf16 v[128:143], v[18:21], v[180:183], v[128:143]
	ds_read_b128 v[18:21], v238 offset:32768
	s_waitcnt lgkmcnt(0)
	v_mfma_f32_32x32x16_bf16 v[144:159], v[18:21], v[176:179], v[144:159]
	ds_read_b128 v[18:21], v238 offset:40960
	s_waitcnt lgkmcnt(0)
	v_mfma_f32_32x32x16_bf16 v[128:143], v[18:21], v[176:179], v[128:143]
	ds_read_b128 v[18:21], v235 offset:32896
	s_waitcnt lgkmcnt(0)
	v_mfma_f32_32x32x16_bf16 v[144:159], v[18:21], v[172:175], v[144:159]
	ds_read_b128 v[18:21], v235 offset:41088
	s_waitcnt lgkmcnt(0)
	v_mfma_f32_32x32x16_bf16 v[128:143], v[18:21], v[172:175], v[128:143]
	ds_read_b128 v[18:21], v236 offset:32896
	s_waitcnt lgkmcnt(0)
	v_mfma_f32_32x32x16_bf16 v[144:159], v[18:21], v[168:171], v[144:159]
	ds_read_b128 v[18:21], v236 offset:41088
	s_waitcnt lgkmcnt(0)
	v_mfma_f32_32x32x16_bf16 v[128:143], v[18:21], v[168:171], v[128:143]
	ds_read_b128 v[18:21], v237 offset:32896
	s_waitcnt lgkmcnt(0)
	v_mfma_f32_32x32x16_bf16 v[144:159], v[18:21], v[164:167], v[144:159]
	ds_read_b128 v[18:21], v237 offset:41088
	s_waitcnt lgkmcnt(0)
	v_mfma_f32_32x32x16_bf16 v[128:143], v[18:21], v[164:167], v[128:143]
	ds_read_b128 v[18:21], v238 offset:32896
	s_waitcnt lgkmcnt(0)
	v_mfma_f32_32x32x16_bf16 v[144:159], v[18:21], v[160:163], v[144:159]
	ds_read_b128 v[18:21], v238 offset:41088
	s_waitcnt lgkmcnt(0)
	v_mfma_f32_32x32x16_bf16 v[128:143], v[18:21], v[160:163], v[128:143]
	s_branch .LBB0_566

.LBB0_601:
	s_or_b64 exec, exec, s[0:1]
	s_mul_i32 s0, s8, s86
	s_mul_hi_u32 s1, s52, s86
	s_add_i32 s1, s1, s0
	s_mul_i32 s0, s52, s86
	s_lshl_b64 s[0:1], s[0:1], 1
	s_add_u32 s0, s42, s0
	v_mul_lo_u32 v0, v220, s86
	s_addc_u32 s1, s43, s1
	v_or_b32_e32 v0, v0, v219
	v_and_b32_e32 v14, 1, v218
	v_cmp_eq_u32_e32 vcc, 0, v14
	v_lshl_add_u64 v[14:15], v[0:1], 1, s[0:1]
	ds_read_b32 v100, v217
	ds_read_b32 v101, v217 offset:4
	ds_read_b32 v102, v217 offset:8
	ds_read_b32 v103, v217 offset:12
	ds_read_b32 v104, v217 offset:32
	ds_read_b32 v105, v217 offset:36
	ds_read_b32 v106, v217 offset:40
	ds_read_b32 v107, v217 offset:44
	ds_read_b32 v108, v217 offset:64
	ds_read_b32 v109, v217 offset:68
	ds_read_b32 v110, v217 offset:72
	ds_read_b32 v111, v217 offset:76
	ds_read_b32 v112, v217 offset:96
	ds_read_b32 v113, v217 offset:100
	ds_read_b32 v114, v217 offset:104
	ds_read_b32 v115, v217 offset:108
	s_waitcnt lgkmcnt(0)
	v_rcp_f32_e32 v0, v100
	s_nop 0
	v_mul_f32_e32 v17, v80, v0
	v_mul_f32_e32 v18, v64, v0
	v_mul_f32_e32 v19, v48, v0
	v_mul_f32_e32 v20, v32, v0
	v_mov_b32_dpp v21, v17 quad_perm:[1,0,3,2] row_mask:0xf bank_mask:0xf bound_ctrl:1
	v_mov_b32_dpp v22, v18 quad_perm:[1,0,3,2] row_mask:0xf bank_mask:0xf bound_ctrl:1
	v_mov_b32_dpp v23, v19 quad_perm:[1,0,3,2] row_mask:0xf bank_mask:0xf bound_ctrl:1
	v_mov_b32_dpp v24, v20 quad_perm:[1,0,3,2] row_mask:0xf bank_mask:0xf bound_ctrl:1
	v_cvt_pk_bf16_f32 v17, v17, v21
	v_cvt_pk_bf16_f32 v18, v18, v22
	v_cvt_pk_bf16_f32 v19, v19, v23
	v_cvt_pk_bf16_f32 v20, v20, v24
	s_and_saveexec_b64 s[0:1], vcc
	global_store_dword v[14:15], v17, off
	global_store_dword v[14:15], v18, off offset:64
	global_store_dword v[14:15], v19, off offset:128
	global_store_dword v[14:15], v20, off offset:192
	s_or_b64 exec, exec, s[0:1]
	s_cmp_lg_u64 s[26:27], 0
	s_cbranch_scc1 .Lq_nopf
	s_and_saveexec_b64 s[0:1], s[96:97]
	s_cbranch_execz .Lq_pf_skip
	v_mov_b32_e32 v25, 1
	global_atomic_add v25, v1, v25, s[2:3] sc0

.Lq_nopf:
	v_lshl_add_u64 v[14:15], s[86:87], 1, v[14:15]
	v_rcp_f32_e32 v0, v101
	s_nop 0
	v_mul_f32_e32 v17, v81, v0
	v_mul_f32_e32 v18, v65, v0
	v_mul_f32_e32 v19, v49, v0
	v_mul_f32_e32 v20, v33, v0
	v_mov_b32_dpp v21, v17 quad_perm:[1,0,3,2] row_mask:0xf bank_mask:0xf bound_ctrl:1
	v_mov_b32_dpp v22, v18 quad_perm:[1,0,3,2] row_mask:0xf bank_mask:0xf bound_ctrl:1
	v_mov_b32_dpp v23, v19 quad_perm:[1,0,3,2] row_mask:0xf bank_mask:0xf bound_ctrl:1
	v_mov_b32_dpp v24, v20 quad_perm:[1,0,3,2] row_mask:0xf bank_mask:0xf bound_ctrl:1
	v_cvt_pk_bf16_f32 v17, v17, v21
	v_cvt_pk_bf16_f32 v18, v18, v22
	v_cvt_pk_bf16_f32 v19, v19, v23
	v_cvt_pk_bf16_f32 v20, v20, v24
	s_and_saveexec_b64 s[0:1], vcc
	global_store_dword v[14:15], v17, off
	global_store_dword v[14:15], v18, off offset:64
	global_store_dword v[14:15], v19, off offset:128
	global_store_dword v[14:15], v20, off offset:192
	s_or_b64 exec, exec, s[0:1]
	s_lshl_b64 s[0:1], s[86:87], 1
	v_lshl_add_u64 v[14:15], v[14:15], 0, s[0:1]
	v_rcp_f32_e32 v0, v102
	s_nop 0
	v_mul_f32_e32 v17, v82, v0
	v_mul_f32_e32 v18, v66, v0
	v_mul_f32_e32 v19, v50, v0
	v_mul_f32_e32 v20, v34, v0
	v_mov_b32_dpp v21, v17 quad_perm:[1,0,3,2] row_mask:0xf bank_mask:0xf bound_ctrl:1
	v_mov_b32_dpp v22, v18 quad_perm:[1,0,3,2] row_mask:0xf bank_mask:0xf bound_ctrl:1
	v_mov_b32_dpp v23, v19 quad_perm:[1,0,3,2] row_mask:0xf bank_mask:0xf bound_ctrl:1
	v_mov_b32_dpp v24, v20 quad_perm:[1,0,3,2] row_mask:0xf bank_mask:0xf bound_ctrl:1
	v_cvt_pk_bf16_f32 v17, v17, v21
	v_cvt_pk_bf16_f32 v18, v18, v22
	v_cvt_pk_bf16_f32 v19, v19, v23
	v_cvt_pk_bf16_f32 v20, v20, v24
	s_and_saveexec_b64 s[22:23], vcc
	global_store_dword v[14:15], v17, off
	global_store_dword v[14:15], v18, off offset:64
	global_store_dword v[14:15], v19, off offset:128
	global_store_dword v[14:15], v20, off offset:192
	s_or_b64 exec, exec, s[22:23]
	v_lshl_add_u64 v[14:15], v[14:15], 0, s[0:1]
	v_rcp_f32_e32 v0, v103
	s_nop 0
	v_mul_f32_e32 v17, v83, v0
	v_mul_f32_e32 v18, v67, v0
	v_mul_f32_e32 v19, v51, v0
	v_mul_f32_e32 v20, v35, v0
	v_mov_b32_dpp v21, v17 quad_perm:[1,0,3,2] row_mask:0xf bank_mask:0xf bound_ctrl:1
	v_mov_b32_dpp v22, v18 quad_perm:[1,0,3,2] row_mask:0xf bank_mask:0xf bound_ctrl:1
	v_mov_b32_dpp v23, v19 quad_perm:[1,0,3,2] row_mask:0xf bank_mask:0xf bound_ctrl:1
	v_mov_b32_dpp v24, v20 quad_perm:[1,0,3,2] row_mask:0xf bank_mask:0xf bound_ctrl:1
	v_cvt_pk_bf16_f32 v17, v17, v21
	v_cvt_pk_bf16_f32 v18, v18, v22
	v_cvt_pk_bf16_f32 v19, v19, v23
	v_cvt_pk_bf16_f32 v20, v20, v24
	s_and_saveexec_b64 s[22:23], vcc
	global_store_dword v[14:15], v17, off
	global_store_dword v[14:15], v18, off offset:64
	global_store_dword v[14:15], v19, off offset:128
	global_store_dword v[14:15], v20, off offset:192
	s_or_b64 exec, exec, s[22:23]
	v_mad_u64_u32 v[14:15], s[8:9], s86, 10, v[14:15]
	v_rcp_f32_e32 v0, v104
	s_nop 0
	v_mul_f32_e32 v17, v84, v0
	v_mul_f32_e32 v18, v68, v0
	v_mul_f32_e32 v19, v52, v0
	v_mul_f32_e32 v20, v36, v0
	v_mov_b32_dpp v21, v17 quad_perm:[1,0,3,2] row_mask:0xf bank_mask:0xf bound_ctrl:1
	v_mov_b32_dpp v22, v18 quad_perm:[1,0,3,2] row_mask:0xf bank_mask:0xf bound_ctrl:1
	v_mov_b32_dpp v23, v19 quad_perm:[1,0,3,2] row_mask:0xf bank_mask:0xf bound_ctrl:1
	v_mov_b32_dpp v24, v20 quad_perm:[1,0,3,2] row_mask:0xf bank_mask:0xf bound_ctrl:1
	v_cvt_pk_bf16_f32 v17, v17, v21
	v_cvt_pk_bf16_f32 v18, v18, v22
	v_cvt_pk_bf16_f32 v19, v19, v23
	v_cvt_pk_bf16_f32 v20, v20, v24
	s_and_saveexec_b64 s[22:23], vcc
	global_store_dword v[14:15], v17, off
	global_store_dword v[14:15], v18, off offset:64
	global_store_dword v[14:15], v19, off offset:128
	global_store_dword v[14:15], v20, off offset:192
	s_or_b64 exec, exec, s[22:23]
	v_lshl_add_u64 v[14:15], v[14:15], 0, s[0:1]
	v_rcp_f32_e32 v0, v105
	s_nop 0
	v_mul_f32_e32 v17, v85, v0
	v_mul_f32_e32 v18, v69, v0
	v_mul_f32_e32 v19, v53, v0
	v_mul_f32_e32 v20, v37, v0
	v_mov_b32_dpp v21, v17 quad_perm:[1,0,3,2] row_mask:0xf bank_mask:0xf bound_ctrl:1
	v_mov_b32_dpp v22, v18 quad_perm:[1,0,3,2] row_mask:0xf bank_mask:0xf bound_ctrl:1
	v_mov_b32_dpp v23, v19 quad_perm:[1,0,3,2] row_mask:0xf bank_mask:0xf bound_ctrl:1
	v_mov_b32_dpp v24, v20 quad_perm:[1,0,3,2] row_mask:0xf bank_mask:0xf bound_ctrl:1
	v_cvt_pk_bf16_f32 v17, v17, v21
	v_cvt_pk_bf16_f32 v18, v18, v22
	v_cvt_pk_bf16_f32 v19, v19, v23
	v_cvt_pk_bf16_f32 v20, v20, v24
	s_and_saveexec_b64 s[22:23], vcc
	global_store_dword v[14:15], v17, off
	global_store_dword v[14:15], v18, off offset:64
	global_store_dword v[14:15], v19, off offset:128
	global_store_dword v[14:15], v20, off offset:192
	s_or_b64 exec, exec, s[22:23]
	v_lshl_add_u64 v[14:15], v[14:15], 0, s[0:1]
	v_rcp_f32_e32 v0, v106
	s_nop 0
	v_mul_f32_e32 v17, v86, v0
	v_mul_f32_e32 v18, v70, v0
	v_mul_f32_e32 v19, v54, v0
	v_mul_f32_e32 v20, v38, v0
	v_mov_b32_dpp v21, v17 quad_perm:[1,0,3,2] row_mask:0xf bank_mask:0xf bound_ctrl:1
	v_mov_b32_dpp v22, v18 quad_perm:[1,0,3,2] row_mask:0xf bank_mask:0xf bound_ctrl:1
	v_mov_b32_dpp v23, v19 quad_perm:[1,0,3,2] row_mask:0xf bank_mask:0xf bound_ctrl:1
	v_mov_b32_dpp v24, v20 quad_perm:[1,0,3,2] row_mask:0xf bank_mask:0xf bound_ctrl:1
	v_cvt_pk_bf16_f32 v17, v17, v21
	v_cvt_pk_bf16_f32 v18, v18, v22
	v_cvt_pk_bf16_f32 v19, v19, v23
	v_cvt_pk_bf16_f32 v20, v20, v24
	s_and_saveexec_b64 s[22:23], vcc
	global_store_dword v[14:15], v17, off
	global_store_dword v[14:15], v18, off offset:64
	global_store_dword v[14:15], v19, off offset:128
	global_store_dword v[14:15], v20, off offset:192
	s_or_b64 exec, exec, s[22:23]
	v_lshl_add_u64 v[14:15], v[14:15], 0, s[0:1]
	v_rcp_f32_e32 v0, v107
	s_nop 0
	v_mul_f32_e32 v17, v87, v0
	v_mul_f32_e32 v18, v71, v0
	v_mul_f32_e32 v19, v55, v0
	v_mul_f32_e32 v20, v39, v0
	v_mov_b32_dpp v21, v17 quad_perm:[1,0,3,2] row_mask:0xf bank_mask:0xf bound_ctrl:1
	v_mov_b32_dpp v22, v18 quad_perm:[1,0,3,2] row_mask:0xf bank_mask:0xf bound_ctrl:1
	v_mov_b32_dpp v23, v19 quad_perm:[1,0,3,2] row_mask:0xf bank_mask:0xf bound_ctrl:1
	v_mov_b32_dpp v24, v20 quad_perm:[1,0,3,2] row_mask:0xf bank_mask:0xf bound_ctrl:1
	v_cvt_pk_bf16_f32 v17, v17, v21
	v_cvt_pk_bf16_f32 v18, v18, v22
	v_cvt_pk_bf16_f32 v19, v19, v23
	v_cvt_pk_bf16_f32 v20, v20, v24
	s_and_saveexec_b64 s[22:23], vcc
	global_store_dword v[14:15], v17, off
	global_store_dword v[14:15], v18, off offset:64
	global_store_dword v[14:15], v19, off offset:128
	global_store_dword v[14:15], v20, off offset:192
	s_or_b64 exec, exec, s[22:23]
	s_mul_hi_u32 s23, s86, 10
	s_mul_i32 s22, s86, 10
	v_lshl_add_u64 v[14:15], v[14:15], 0, s[22:23]
	v_rcp_f32_e32 v0, v108
	s_nop 0
	v_mul_f32_e32 v17, v88, v0
	v_mul_f32_e32 v18, v72, v0
	v_mul_f32_e32 v19, v56, v0
	v_mul_f32_e32 v20, v40, v0
	v_mov_b32_dpp v21, v17 quad_perm:[1,0,3,2] row_mask:0xf bank_mask:0xf bound_ctrl:1
	v_mov_b32_dpp v22, v18 quad_perm:[1,0,3,2] row_mask:0xf bank_mask:0xf bound_ctrl:1
	v_mov_b32_dpp v23, v19 quad_perm:[1,0,3,2] row_mask:0xf bank_mask:0xf bound_ctrl:1
	v_mov_b32_dpp v24, v20 quad_perm:[1,0,3,2] row_mask:0xf bank_mask:0xf bound_ctrl:1
	v_cvt_pk_bf16_f32 v17, v17, v21
	v_cvt_pk_bf16_f32 v18, v18, v22
	v_cvt_pk_bf16_f32 v19, v19, v23
	v_cvt_pk_bf16_f32 v20, v20, v24
	s_and_saveexec_b64 s[24:25], vcc
	global_store_dword v[14:15], v17, off
	global_store_dword v[14:15], v18, off offset:64
	global_store_dword v[14:15], v19, off offset:128
	global_store_dword v[14:15], v20, off offset:192
	s_or_b64 exec, exec, s[24:25]
	v_lshl_add_u64 v[14:15], v[14:15], 0, s[0:1]
	v_rcp_f32_e32 v0, v109
	s_nop 0
	v_mul_f32_e32 v17, v89, v0
	v_mul_f32_e32 v18, v73, v0
	v_mul_f32_e32 v19, v57, v0
	v_mul_f32_e32 v20, v41, v0
	v_mov_b32_dpp v21, v17 quad_perm:[1,0,3,2] row_mask:0xf bank_mask:0xf bound_ctrl:1
	v_mov_b32_dpp v22, v18 quad_perm:[1,0,3,2] row_mask:0xf bank_mask:0xf bound_ctrl:1
	v_mov_b32_dpp v23, v19 quad_perm:[1,0,3,2] row_mask:0xf bank_mask:0xf bound_ctrl:1
	v_mov_b32_dpp v24, v20 quad_perm:[1,0,3,2] row_mask:0xf bank_mask:0xf bound_ctrl:1
	v_cvt_pk_bf16_f32 v17, v17, v21
	v_cvt_pk_bf16_f32 v18, v18, v22
	v_cvt_pk_bf16_f32 v19, v19, v23
	v_cvt_pk_bf16_f32 v20, v20, v24
	s_and_saveexec_b64 s[24:25], vcc
	global_store_dword v[14:15], v17, off
	global_store_dword v[14:15], v18, off offset:64
	global_store_dword v[14:15], v19, off offset:128
	global_store_dword v[14:15], v20, off offset:192
	s_or_b64 exec, exec, s[24:25]
	v_lshl_add_u64 v[14:15], v[14:15], 0, s[0:1]
	v_rcp_f32_e32 v0, v110
	s_nop 0
	v_mul_f32_e32 v17, v90, v0
	v_mul_f32_e32 v18, v74, v0
	v_mul_f32_e32 v19, v58, v0
	v_mul_f32_e32 v20, v42, v0
	v_mov_b32_dpp v21, v17 quad_perm:[1,0,3,2] row_mask:0xf bank_mask:0xf bound_ctrl:1
	v_mov_b32_dpp v22, v18 quad_perm:[1,0,3,2] row_mask:0xf bank_mask:0xf bound_ctrl:1
	v_mov_b32_dpp v23, v19 quad_perm:[1,0,3,2] row_mask:0xf bank_mask:0xf bound_ctrl:1
	v_mov_b32_dpp v24, v20 quad_perm:[1,0,3,2] row_mask:0xf bank_mask:0xf bound_ctrl:1
	v_cvt_pk_bf16_f32 v17, v17, v21
	v_cvt_pk_bf16_f32 v18, v18, v22
	v_cvt_pk_bf16_f32 v19, v19, v23
	v_cvt_pk_bf16_f32 v20, v20, v24
	s_and_saveexec_b64 s[24:25], vcc
	global_store_dword v[14:15], v17, off
	global_store_dword v[14:15], v18, off offset:64
	global_store_dword v[14:15], v19, off offset:128
	global_store_dword v[14:15], v20, off offset:192
	s_or_b64 exec, exec, s[24:25]
	v_lshl_add_u64 v[14:15], v[14:15], 0, s[0:1]
	v_rcp_f32_e32 v0, v111
	s_nop 0
	v_mul_f32_e32 v17, v91, v0
	v_mul_f32_e32 v18, v75, v0
	v_mul_f32_e32 v19, v59, v0
	v_mul_f32_e32 v20, v43, v0
	v_mov_b32_dpp v21, v17 quad_perm:[1,0,3,2] row_mask:0xf bank_mask:0xf bound_ctrl:1
	v_mov_b32_dpp v22, v18 quad_perm:[1,0,3,2] row_mask:0xf bank_mask:0xf bound_ctrl:1
	v_mov_b32_dpp v23, v19 quad_perm:[1,0,3,2] row_mask:0xf bank_mask:0xf bound_ctrl:1
	v_mov_b32_dpp v24, v20 quad_perm:[1,0,3,2] row_mask:0xf bank_mask:0xf bound_ctrl:1
	v_cvt_pk_bf16_f32 v17, v17, v21
	v_cvt_pk_bf16_f32 v18, v18, v22
	v_cvt_pk_bf16_f32 v19, v19, v23
	v_cvt_pk_bf16_f32 v20, v20, v24
	s_and_saveexec_b64 s[24:25], vcc
	global_store_dword v[14:15], v17, off
	global_store_dword v[14:15], v18, off offset:64
	global_store_dword v[14:15], v19, off offset:128
	global_store_dword v[14:15], v20, off offset:192
	s_or_b64 exec, exec, s[24:25]
	v_lshl_add_u64 v[14:15], v[14:15], 0, s[22:23]
	v_rcp_f32_e32 v0, v112
	s_nop 0
	v_mul_f32_e32 v17, v92, v0
	v_mul_f32_e32 v18, v76, v0
	v_mul_f32_e32 v19, v60, v0
	v_mul_f32_e32 v20, v44, v0
	v_mov_b32_dpp v21, v17 quad_perm:[1,0,3,2] row_mask:0xf bank_mask:0xf bound_ctrl:1
	v_mov_b32_dpp v22, v18 quad_perm:[1,0,3,2] row_mask:0xf bank_mask:0xf bound_ctrl:1
	v_mov_b32_dpp v23, v19 quad_perm:[1,0,3,2] row_mask:0xf bank_mask:0xf bound_ctrl:1
	v_mov_b32_dpp v24, v20 quad_perm:[1,0,3,2] row_mask:0xf bank_mask:0xf bound_ctrl:1
	v_cvt_pk_bf16_f32 v17, v17, v21
	v_cvt_pk_bf16_f32 v18, v18, v22
	v_cvt_pk_bf16_f32 v19, v19, v23
	v_cvt_pk_bf16_f32 v20, v20, v24
	s_and_saveexec_b64 s[22:23], vcc
	global_store_dword v[14:15], v17, off
	global_store_dword v[14:15], v18, off offset:64
	global_store_dword v[14:15], v19, off offset:128
	global_store_dword v[14:15], v20, off offset:192
	s_or_b64 exec, exec, s[22:23]
	v_lshl_add_u64 v[14:15], v[14:15], 0, s[0:1]
	v_rcp_f32_e32 v0, v113
	s_nop 0
	v_mul_f32_e32 v17, v93, v0
	v_mul_f32_e32 v18, v77, v0
	v_mul_f32_e32 v19, v61, v0
	v_mul_f32_e32 v20, v45, v0
	v_mov_b32_dpp v21, v17 quad_perm:[1,0,3,2] row_mask:0xf bank_mask:0xf bound_ctrl:1
	v_mov_b32_dpp v22, v18 quad_perm:[1,0,3,2] row_mask:0xf bank_mask:0xf bound_ctrl:1
	v_mov_b32_dpp v23, v19 quad_perm:[1,0,3,2] row_mask:0xf bank_mask:0xf bound_ctrl:1
	v_mov_b32_dpp v24, v20 quad_perm:[1,0,3,2] row_mask:0xf bank_mask:0xf bound_ctrl:1
	v_cvt_pk_bf16_f32 v17, v17, v21
	v_cvt_pk_bf16_f32 v18, v18, v22
	v_cvt_pk_bf16_f32 v19, v19, v23
	v_cvt_pk_bf16_f32 v20, v20, v24
	s_and_saveexec_b64 s[22:23], vcc
	global_store_dword v[14:15], v17, off
	global_store_dword v[14:15], v18, off offset:64
	global_store_dword v[14:15], v19, off offset:128
	global_store_dword v[14:15], v20, off offset:192
	s_or_b64 exec, exec, s[22:23]
	v_lshl_add_u64 v[14:15], v[14:15], 0, s[0:1]
	v_rcp_f32_e32 v0, v114
	s_nop 0
	v_mul_f32_e32 v17, v94, v0
	v_mul_f32_e32 v18, v78, v0
	v_mul_f32_e32 v19, v62, v0
	v_mul_f32_e32 v20, v46, v0
	v_mov_b32_dpp v21, v17 quad_perm:[1,0,3,2] row_mask:0xf bank_mask:0xf bound_ctrl:1
	v_mov_b32_dpp v22, v18 quad_perm:[1,0,3,2] row_mask:0xf bank_mask:0xf bound_ctrl:1
	v_mov_b32_dpp v23, v19 quad_perm:[1,0,3,2] row_mask:0xf bank_mask:0xf bound_ctrl:1
	v_mov_b32_dpp v24, v20 quad_perm:[1,0,3,2] row_mask:0xf bank_mask:0xf bound_ctrl:1
	v_cvt_pk_bf16_f32 v17, v17, v21
	v_cvt_pk_bf16_f32 v18, v18, v22
	v_cvt_pk_bf16_f32 v19, v19, v23
	v_cvt_pk_bf16_f32 v20, v20, v24
	s_and_saveexec_b64 s[22:23], vcc
	global_store_dword v[14:15], v17, off
	global_store_dword v[14:15], v18, off offset:64
	global_store_dword v[14:15], v19, off offset:128
	global_store_dword v[14:15], v20, off offset:192
	s_or_b64 exec, exec, s[22:23]
	v_lshl_add_u64 v[14:15], v[14:15], 0, s[0:1]
	v_rcp_f32_e32 v0, v115
	s_nop 0
	v_mul_f32_e32 v17, v95, v0
	v_mul_f32_e32 v18, v79, v0
	v_mul_f32_e32 v19, v63, v0
	v_mul_f32_e32 v20, v47, v0
	v_mov_b32_dpp v21, v17 quad_perm:[1,0,3,2] row_mask:0xf bank_mask:0xf bound_ctrl:1
	v_mov_b32_dpp v22, v18 quad_perm:[1,0,3,2] row_mask:0xf bank_mask:0xf bound_ctrl:1
	v_mov_b32_dpp v23, v19 quad_perm:[1,0,3,2] row_mask:0xf bank_mask:0xf bound_ctrl:1
	v_mov_b32_dpp v24, v20 quad_perm:[1,0,3,2] row_mask:0xf bank_mask:0xf bound_ctrl:1
	v_cvt_pk_bf16_f32 v17, v17, v21
	v_cvt_pk_bf16_f32 v18, v18, v22
	v_cvt_pk_bf16_f32 v19, v19, v23
	v_cvt_pk_bf16_f32 v20, v20, v24
	s_and_saveexec_b64 s[0:1], vcc
	global_store_dword v[14:15], v17, off
	global_store_dword v[14:15], v18, off offset:64
	global_store_dword v[14:15], v19, off offset:128
	global_store_dword v[14:15], v20, off offset:192
	s_or_b64 exec, exec, s[0:1]
	s_branch .LBB0_505
